# combined: barrier early-invalidate, PE gate loads in flight, PD ml prologue/epilogue de-serialized, ml inner loop softmax-weight part branchless with batched LDS reads
# speedup vs baseline: 1.0191x; 1.0018x over previous
.LBB0_221:
	s_and_b64 vcc, exec, s[0:1]
	s_cbranch_vccz .LBB0_198
	s_ashr_i32 s0, s16, 3
	s_bfe_u32 s1, s16, 0x20008
	s_xor_b32 s19, s1, s0
	s_lshr_b32 s0, s0, 30
	s_and_b32 s13, s16, 7
	v_mov_b32_e32 v97, v167
	s_add_i32 s0, s19, s0
	s_ashr_i32 s17, s0, 2
	v_ashrrev_i32_e32 v94, 3, v97
	s_lshl_b32 s34, s13, 8
	s_and_b32 s0, s0, -4
	s_lshl_b32 s8, s17, 8
	v_add_u32_e32 v22, s34, v94
	v_mov_b64_e32 v[16:17], s[78:79]
	s_sub_i32 s18, s19, s0
	v_mad_i64_i32 v[72:73], s[0:1], v22, s37, v[16:17]
	s_ashr_i32 s9, s8, 31
	v_add_u32_e32 v10, 64, v22
	v_add_u32_e32 v20, 0x80, v22
	v_add_u32_e32 v22, 0xc0, v22
	s_lshl_b64 s[0:1], s[8:9], 1
	v_mad_i64_i32 v[74:75], s[10:11], v10, s37, v[16:17]
	v_mad_i64_i32 v[78:79], s[10:11], v20, s37, v[16:17]
	v_mad_i64_i32 v[84:85], s[10:11], v22, s37, v[16:17]
	v_lshl_add_u64 v[8:9], v[72:73], 0, s[0:1]
	v_lshl_add_u64 v[10:11], v[74:75], 0, s[0:1]
	v_lshl_add_u64 v[20:21], v[78:79], 0, s[0:1]
	v_lshl_add_u64 v[16:17], v[84:85], 0, s[0:1]
	s_lshl_b32 s0, s13, 5
	s_add_i32 s0, s17, s0
	s_ashr_i32 s1, s0, 31
	v_ashrrev_i32_e32 v98, 4, v97
	v_lshlrev_b32_e32 v0, 3, v97
	s_lshl_b64 s[10:11], s[0:1], 16
	v_readfirstlane_b32 s12, v97
	v_and_b32_e32 v4, 0x78, v0
	v_add_u32_e32 v0, s8, v98
	s_add_u32 s10, s76, s10
	s_waitcnt lgkmcnt(0)
	v_ashrrev_i32_e32 v1, 31, v0
	s_addc_u32 s11, s77, s11
	s_ashr_i32 s9, s12, 1
	v_and_b32_e32 v96, 15, v97
	v_lshlrev_b64 v[2:3], 11, v[0:1]
	v_add_u32_e32 v0, 32, v0
	s_and_b32 s17, s9, 0xffffffe0
	v_ashrrev_i32_e32 v1, 31, v0
	v_or_b32_e32 v76, s17, v96
	v_lshlrev_b64 v[0:1], 11, v[0:1]
	v_ashrrev_i32_e32 v77, 31, v76
	v_bfe_u32 v95, v97, 4, 2
	v_and_b32_e32 v64, 7, v97
	v_lshl_add_u64 v[2:3], s[62:63], 0, v[2:3]
	s_mov_b32 s35, s29
	v_lshl_add_u64 v[0:1], s[62:63], 0, v[0:1]
	v_lshlrev_b64 v[24:25], 8, v[76:77]
	v_lshl_add_u64 v[2:3], v[2:3], 0, s[34:35]
	v_lshlrev_b32_e32 v156, 1, v4
	v_lshl_add_u64 v[0:1], v[0:1], 0, s[34:35]
	v_lshlrev_b32_e32 v18, 4, v64
	v_mov_b32_e32 v19, v157
	v_lshl_add_u64 v[24:25], s[10:11], 0, v[24:25]
	v_lshlrev_b32_e32 v26, 4, v95
	v_mov_b32_e32 v27, v157
	v_lshl_add_u64 v[2:3], v[2:3], 0, v[156:157]
	v_lshl_add_u64 v[4:5], v[0:1], 0, v[156:157]
	v_lshl_add_u64 v[8:9], v[8:9], 0, v[18:19]
	v_lshl_add_u64 v[12:13], v[10:11], 0, v[18:19]
	v_lshl_add_u64 v[20:21], v[20:21], 0, v[18:19]
	v_lshl_add_u64 v[22:23], v[16:17], 0, v[18:19]
	v_lshl_add_u64 v[28:29], v[24:25], 0, v[26:27]
	s_movk_i32 s1, 0x1000
	s_add_i32 s10, s0, 0x8200
	global_load_dwordx4 v[0:3], v[2:3], off
	s_nop 0
	global_load_dwordx4 v[4:7], v[4:5], off
	s_nop 0
	global_load_dwordx4 v[8:11], v[8:9], off
	s_nop 0
	global_load_dwordx4 v[12:15], v[12:13], off
	s_nop 0
	global_load_dwordx4 v[16:19], v[20:21], off
	s_nop 0
	global_load_dwordx4 v[20:23], v[22:23], off
	s_nop 0
	global_load_dwordx4 v[48:51], v[28:29], off
	global_load_dwordx4 v[40:43], v[28:29], off offset:64
	global_load_dwordx4 v[32:35], v[28:29], off offset:128
	global_load_dwordx4 v[24:27], v[28:29], off offset:192
	v_add_co_u32_e32 v28, vcc, s1, v28
	s_ashr_i32 s11, s10, 31
	s_nop 0
	v_addc_co_u32_e32 v29, vcc, 0, v29, vcc
	s_lshl_b64 s[10:11], s[10:11], 2
	global_load_dwordx4 v[52:55], v[28:29], off
	global_load_dwordx4 v[44:47], v[28:29], off offset:64
	global_load_dwordx4 v[36:39], v[28:29], off offset:128
	s_nop 0
	global_load_dwordx4 v[28:31], v[28:29], off offset:192
	s_add_u32 s10, s70, s10
	s_addc_u32 s11, s71, s11
	global_load_dword v100, v157, s[10:11]
	s_lshl_b32 s1, s18, 6
	s_add_i32 s1, s1, 64
	v_cmp_gt_i32_e32 vcc, s1, v97
	v_lshl_add_u32 v99, v97, 2, 16
	s_and_saveexec_b64 s[10:11], vcc
	s_cbranch_execz .LBB0_224
	s_lshl_b32 s1, s13, 13
	s_add_i32 s1, s8, s1
	s_add_i32 s1, s1, 0x10000
	v_add_u32_e32 v136, s1, v97
	v_ashrrev_i32_e32 v137, 31, v136
	v_lshl_add_u64 v[136:137], v[136:137], 2, s[26:27]
	global_load_dword v138, v[136:137], off
.LBB0_224:
	s_or_b64 exec, exec, s[10:11]
	v_and_b32_e32 v139, 0xffffffc0, v97
	s_movk_i32 s1, 0x100
	s_lshl_b32 s19, s19, 6
	v_cmp_eq_u32_e32 vcc, s1, v139
	s_and_saveexec_b64 s[10:11], vcc
	s_cbranch_execz .LBB0_226
	s_lshl_b32 s1, s13, 13
	s_add_i32 s1, s19, s1
	v_add_u32_e32 v140, 0xffffff00, v97
	s_add_i32 s20, s1, 0x20000
	v_or_b32_e32 v142, s20, v140
	v_ashrrev_i32_e32 v143, 31, v142
	v_lshl_add_u64 v[142:143], v[142:143], 2, s[26:27]
	global_load_dword v141, v[142:143], off
	v_or_b32_e32 v142, s1, v140
	v_ashrrev_i32_e32 v143, 31, v142
	v_lshl_add_u64 v[142:143], v[142:143], 2, s[26:27]
	global_load_dword v144, v[142:143], off
.LBB0_226:
	s_or_b64 exec, exec, s[10:11]
	v_add_u32_e32 v60, s19, v98
	v_ashrrev_i32_e32 v61, 31, v60
	v_lshlrev_b64 v[56:57], 11, v[60:61]
	v_add_u32_e32 v60, 32, v60
	v_add_u32_e32 v80, s19, v94
	v_ashrrev_i32_e32 v61, 31, v60
	v_ashrrev_i32_e32 v81, 31, v80
	s_lshl_b32 s1, s13, 7
	v_lshlrev_b64 v[60:61], 11, v[60:61]
	v_lshlrev_b64 v[66:67], 11, v[80:81]
	v_lshl_add_u64 v[56:57], s[66:67], 0, v[56:57]
	s_lshl_b32 s28, s1, 1
	v_lshl_add_u64 v[60:61], s[66:67], 0, v[60:61]
	v_lshl_add_u64 v[66:67], s[66:67], 0, v[66:67]
	v_lshl_add_u64 v[56:57], v[56:57], 0, s[28:29]
	v_lshl_add_u64 v[60:61], v[60:61], 0, s[28:29]
	v_lshl_add_u64 v[66:67], v[66:67], 0, s[28:29]
	v_lshlrev_b32_e32 v68, 5, v64
	v_mov_b32_e32 v69, v157
	v_lshl_add_u64 v[56:57], v[56:57], 0, v[156:157]
	v_lshl_add_u64 v[60:61], v[60:61], 0, v[156:157]
	v_lshl_add_u64 v[70:71], v[66:67], 0, v[68:69]
	global_load_dwordx4 v[56:59], v[56:57], off
	s_lshl_b32 s0, s0, 7
	global_load_dwordx4 v[60:63], v[60:61], off
	s_nop 0
	global_load_dwordx4 v[66:69], v[70:71], off offset:16
	global_load_dwordx4 v[86:89], v[70:71], off
	s_ashr_i32 s1, s0, 31
	s_lshl_b64 s[0:1], s[0:1], 2
	v_readlane_b32 s10, v251, 55
	v_readlane_b32 s11, v251, 56
	s_add_u32 s0, s10, s0
	s_addc_u32 s1, s11, s1
	v_lshlrev_b32_e32 v65, 6, v64
	global_load_dwordx4 v[148:151], v65, s[0:1] offset:48
	global_load_dwordx4 v[152:155], v65, s[0:1] offset:32
	global_load_dwordx4 v[90:93], v65, s[0:1] offset:16
	global_load_dwordx4 v[102:105], v65, s[0:1]
	s_waitcnt vmcnt(0)
	s_lshl_b32 s1, s18, 6
	s_add_i32 s1, s1, 64
	v_cmp_gt_i32_e32 vcc, s1, v97
	s_and_saveexec_b64 s[10:11], vcc
	v_add_u32_e32 v136, 0x23400, v99
	ds_write_b32 v136, v138
	s_or_b64 exec, exec, s[10:11]
	v_and_b32_e32 v139, 0xffffffc0, v97
	s_movk_i32 s1, 0x100
	v_cmp_eq_u32_e32 vcc, s1, v139
	s_and_saveexec_b64 s[10:11], vcc
	v_max_f32_e32 v136, v100, v100
	v_lshl_add_u32 v140, v140, 2, 16
	v_add_u32_e32 v137, 0x23800, v140
	v_max_f32_e32 v141, v141, v141
	v_max_f32_e32 v136, v141, v136
	ds_write_b32 v137, v136
	v_add_f32_e32 v144, v136, v144
	v_add_u32_e32 v136, 0x23900, v140
	ds_write_b32 v136, v144
	s_or_b64 exec, exec, s[10:11]
	v_cmp_lt_i32_e32 vcc, v188, v187
	v_lshlrev_b32_e32 v108, 16, v66
	v_lshlrev_b32_e32 v70, 16, v86
	v_and_b32_e32 v71, 0xffff0000, v86
	v_lshlrev_b32_e32 v77, 16, v87
	v_and_b32_e32 v82, 0xffff0000, v87
	v_lshlrev_b32_e32 v83, 16, v88
	v_and_b32_e32 v101, 0xffff0000, v88
	v_lshlrev_b32_e32 v106, 16, v89
	v_and_b32_e32 v107, 0xffff0000, v89
	v_and_b32_e32 v109, 0xffff0000, v66
	v_lshlrev_b32_e32 v110, 16, v67
	v_and_b32_e32 v111, 0xffff0000, v67
	v_lshlrev_b32_e32 v112, 16, v68
	v_and_b32_e32 v113, 0xffff0000, v68
	v_lshlrev_b32_e32 v114, 16, v69
	v_and_b32_e32 v115, 0xffff0000, v69
	v_mul_f32_e32 v65, v103, v71
	v_fmac_f32_e32 v65, v102, v70
	v_fmac_f32_e32 v65, v104, v77
	v_fmac_f32_e32 v65, v105, v82
	v_fmac_f32_e32 v65, v90, v83
	v_fmac_f32_e32 v65, v91, v101
	v_fmac_f32_e32 v65, v92, v106
	v_fmac_f32_e32 v65, v93, v107
	v_fmac_f32_e32 v65, v152, v108
	v_fmac_f32_e32 v65, v153, v109
	v_fmac_f32_e32 v65, v154, v110
	v_fmac_f32_e32 v65, v155, v111
	v_fmac_f32_e32 v65, v148, v112
	v_fmac_f32_e32 v65, v149, v113
	v_fmac_f32_e32 v65, v150, v114
	v_cndmask_b32_e32 v66, v185, v188, vcc
	v_fmac_f32_e32 v65, v151, v115
	v_lshlrev_b32_e32 v101, 2, v66
	ds_bpermute_b32 v66, v101, v65
	v_cmp_lt_i32_e32 vcc, v189, v187
	s_waitcnt lgkmcnt(0)
	v_add_f32_e32 v65, v65, v66
	v_cndmask_b32_e32 v66, v185, v189, vcc
	v_lshlrev_b32_e32 v102, 2, v66
	ds_bpermute_b32 v66, v102, v65
	v_cmp_lt_i32_e32 vcc, v190, v187
	s_waitcnt lgkmcnt(0)
	v_add_f32_e32 v65, v65, v66
	v_cndmask_b32_e32 v66, v185, v190, vcc
	v_lshlrev_b32_e32 v103, 2, v66
	ds_bpermute_b32 v66, v103, v65
	v_cmp_eq_u32_e32 vcc, 0, v64
	s_and_saveexec_b64 s[0:1], vcc
	s_cbranch_execz .LBB0_228
	s_waitcnt lgkmcnt(0)
	v_add_f32_e32 v65, v65, v66
	v_lshl_add_u32 v66, v94, 2, 16
	v_add_u32_e32 v66, 0x23b00, v66
	ds_write_b32 v66, v65
.LBB0_228:
	s_or_b64 exec, exec, s[0:1]
	s_movk_i32 s0, 0x88
	v_mul_lo_u32 v65, v98, s0
	v_lshlrev_b32_e32 v105, 1, v65
	v_add3_u32 v65, 16, v105, v156
	s_movk_i32 s0, 0x48
	v_lshlrev_b32_e32 v104, 3, v64
	v_lshlrev_b32_e32 v64, 3, v95
	ds_write_b128 v65, v[56:59]
	ds_write_b128 v65, v[60:63] offset:8704
	ds_write_b128 v65, v[0:3] offset:17408
	ds_write_b128 v65, v[4:7] offset:26112
	v_mul_lo_u32 v56, v94, s0
	v_lshlrev_b32_e32 v106, 1, v56
	v_lshlrev_b32_e32 v82, 1, v104
	v_lshl_add_u32 v107, v64, 1, 16
	s_movk_i32 s1, 0x110
	v_add3_u32 v56, 16, v106, v82
	v_mad_u32_u24 v65, v96, s1, v107
	ds_write_b128 v56, v[8:11] offset:34816
	ds_write_b128 v56, v[12:15] offset:44032
	ds_write_b128 v56, v[16:19] offset:53248
	ds_write_b128 v56, v[20:23] offset:62464
	s_waitcnt lgkmcnt(0)
	s_barrier
	ds_read_b128 v[56:59], v65
	ds_read_b128 v[60:63], v65 offset:4352
	ds_read_b128 v[66:69], v65 offset:8704
	ds_read_b128 v[86:89], v65 offset:13056
	s_waitcnt lgkmcnt(3)
	v_mfma_f32_16x16x32_bf16 v[90:93], v[56:59], v[48:51], 0
	s_mov_b32 s19, 0
	v_mov_b32_e32 v83, 0
	s_cmp_lt_i32 s18, 0
	v_mfma_f32_16x16x32_bf16 v[56:59], v[56:59], v[52:55], 0
	v_cmp_gt_i32_e64 s[52:53], 64, v97
	s_waitcnt lgkmcnt(2)
	v_mfma_f32_16x16x32_bf16 v[108:111], v[60:63], v[48:51], 0
	v_mfma_f32_16x16x32_bf16 v[60:63], v[60:63], v[52:55], 0
	s_waitcnt lgkmcnt(1)
	v_mfma_f32_16x16x32_bf16 v[112:115], v[66:69], v[48:51], 0
	v_mfma_f32_16x16x32_bf16 v[66:69], v[66:69], v[52:55], 0
	s_waitcnt lgkmcnt(0)
	v_mfma_f32_16x16x32_bf16 v[48:51], v[86:89], v[48:51], 0
	v_mfma_f32_16x16x32_bf16 v[52:55], v[86:89], v[52:55], 0
	ds_read_b128 v[86:89], v65 offset:64
	ds_read_b128 v[116:119], v65 offset:4416
	ds_read_b128 v[120:123], v65 offset:8768
	ds_read_b128 v[124:127], v65 offset:13120
	s_waitcnt lgkmcnt(3)
	v_mfma_f32_16x16x32_bf16 v[90:93], v[86:89], v[40:43], v[90:93]
	v_mfma_f32_16x16x32_bf16 v[56:59], v[86:89], v[44:47], v[56:59]
	s_waitcnt lgkmcnt(2)
	v_mfma_f32_16x16x32_bf16 v[86:89], v[116:119], v[40:43], v[108:111]
	v_mfma_f32_16x16x32_bf16 v[60:63], v[116:119], v[44:47], v[60:63]
	s_waitcnt lgkmcnt(1)
	v_mfma_f32_16x16x32_bf16 v[108:111], v[120:123], v[40:43], v[112:115]
	v_mfma_f32_16x16x32_bf16 v[66:69], v[120:123], v[44:47], v[66:69]
	s_waitcnt lgkmcnt(0)
	v_mfma_f32_16x16x32_bf16 v[40:43], v[124:127], v[40:43], v[48:51]
	v_mfma_f32_16x16x32_bf16 v[44:47], v[124:127], v[44:47], v[52:55]
	s_nop 1
	ds_read_b128 v[48:51], v65 offset:128
	ds_read_b128 v[52:55], v65 offset:4480
	ds_read_b128 v[112:115], v65 offset:8832
	ds_read_b128 v[116:119], v65 offset:13184
	s_waitcnt lgkmcnt(3)
	v_mfma_f32_16x16x32_bf16 v[90:93], v[48:51], v[32:35], v[90:93]
	v_mfma_f32_16x16x32_bf16 v[48:51], v[48:51], v[36:39], v[56:59]
	s_waitcnt lgkmcnt(2)
	v_mfma_f32_16x16x32_bf16 v[56:59], v[52:55], v[32:35], v[86:89]
	v_mfma_f32_16x16x32_bf16 v[52:55], v[52:55], v[36:39], v[60:63]
	s_waitcnt lgkmcnt(1)
	v_mfma_f32_16x16x32_bf16 v[60:63], v[112:115], v[32:35], v[108:111]
	v_mfma_f32_16x16x32_bf16 v[66:69], v[112:115], v[36:39], v[66:69]
	s_waitcnt lgkmcnt(0)
	v_mfma_f32_16x16x32_bf16 v[86:89], v[116:119], v[32:35], v[40:43]
	v_mfma_f32_16x16x32_bf16 v[108:111], v[116:119], v[36:39], v[44:47]
	ds_read_b128 v[32:35], v65 offset:192
	s_nop 0
	ds_read_b128 v[40:43], v65 offset:4544
	ds_read_b128 v[44:47], v65 offset:8896
	ds_read_b128 v[112:115], v65 offset:13248
	s_waitcnt lgkmcnt(3)
	v_mfma_f32_16x16x32_bf16 v[90:93], v[32:35], v[24:27], v[90:93]
	v_mfma_f32_16x16x32_bf16 v[116:119], v[32:35], v[28:31], v[48:51]
	s_waitcnt lgkmcnt(2)
	v_mfma_f32_16x16x32_bf16 v[36:39], v[40:43], v[24:27], v[56:59]
	v_mfma_f32_16x16x32_bf16 v[48:51], v[40:43], v[28:31], v[52:55]
	s_waitcnt lgkmcnt(1)
	v_mfma_f32_16x16x32_bf16 v[32:35], v[44:47], v[24:27], v[60:63]
	v_mfma_f32_16x16x32_bf16 v[40:43], v[44:47], v[28:31], v[66:69]
	s_waitcnt lgkmcnt(0)
	v_mfma_f32_16x16x32_bf16 v[44:47], v[112:115], v[24:27], v[86:89]
	v_lshl_add_u32 v24, v95, 4, 16
	v_add_u32_e32 v60, 0x23800, v24
	ds_read_b128 v[24:27], v60
	ds_read_b128 v[56:59], v60 offset:64
	v_mfma_f32_16x16x32_bf16 v[52:55], v[112:115], v[28:31], v[108:111]
	s_waitcnt lgkmcnt(1)
	v_sub_f32_e32 v24, v100, v24
	s_waitcnt lgkmcnt(0)
	v_sub_f32_e32 v56, v100, v56
	v_sub_f32_e32 v57, v100, v57
	v_sub_f32_e32 v58, v100, v58
	v_sub_f32_e32 v59, v100, v59
	v_mul_f32_e32 v56, 0x3fb8aa3b, v56
	v_mul_f32_e32 v57, 0x3fb8aa3b, v57
	v_mul_f32_e32 v58, 0x3fb8aa3b, v58
	v_mul_f32_e32 v59, 0x3fb8aa3b, v59
	v_exp_f32_e32 v56, v56
	v_exp_f32_e32 v57, v57
	v_exp_f32_e32 v58, v58
	v_exp_f32_e32 v59, v59
	v_mul_f32_e32 v24, 0x3fb8aa3b, v24
	v_pk_mul_f32 v[36:37], v[36:37], v[56:57]
	v_pk_mul_f32 v[48:49], v[48:49], v[56:57]
	v_pk_mul_f32 v[38:39], v[38:39], v[58:59]
	v_pk_mul_f32 v[50:51], v[50:51], v[58:59]
	ds_read_b128 v[56:59], v60 offset:128
	v_exp_f32_e32 v28, v24
	v_sub_f32_e32 v24, v100, v25
	v_mul_f32_e32 v24, 0x3fb8aa3b, v24
	v_exp_f32_e32 v29, v24
	s_waitcnt lgkmcnt(0)
	v_sub_f32_e32 v56, v100, v56
	v_sub_f32_e32 v57, v100, v57
	v_sub_f32_e32 v58, v100, v58
	v_sub_f32_e32 v59, v100, v59
	v_mul_f32_e32 v56, 0x3fb8aa3b, v56
	v_mul_f32_e32 v57, 0x3fb8aa3b, v57
	v_mul_f32_e32 v58, 0x3fb8aa3b, v58
	v_mul_f32_e32 v59, 0x3fb8aa3b, v59
	v_exp_f32_e32 v56, v56
	v_exp_f32_e32 v57, v57
	v_exp_f32_e32 v58, v58
	v_exp_f32_e32 v59, v59
	v_sub_f32_e32 v24, v100, v26
	v_pk_mul_f32 v[32:33], v[32:33], v[56:57]
	v_pk_mul_f32 v[40:41], v[40:41], v[56:57]
	v_pk_mul_f32 v[34:35], v[34:35], v[58:59]
	v_pk_mul_f32 v[42:43], v[42:43], v[58:59]
	ds_read_b128 v[56:59], v60 offset:192
	v_mul_f32_e32 v24, 0x3fb8aa3b, v24
	v_exp_f32_e32 v30, v24
	v_sub_f32_e32 v24, v100, v27
	v_mul_f32_e32 v24, 0x3fb8aa3b, v24
	s_waitcnt lgkmcnt(0)
	v_sub_f32_e32 v56, v100, v56
	v_sub_f32_e32 v57, v100, v57
	v_sub_f32_e32 v58, v100, v58
	v_sub_f32_e32 v59, v100, v59
	v_mul_f32_e32 v56, 0x3fb8aa3b, v56
	v_mul_f32_e32 v57, 0x3fb8aa3b, v57
	v_mul_f32_e32 v58, 0x3fb8aa3b, v58
	v_mul_f32_e32 v59, 0x3fb8aa3b, v59
	v_exp_f32_e32 v31, v24
	v_exp_f32_e32 v56, v56
	v_exp_f32_e32 v57, v57
	v_exp_f32_e32 v58, v58
	v_exp_f32_e32 v59, v59
	v_pk_mul_f32 v[24:25], v[90:91], v[28:29]
	v_pk_mul_f32 v[26:27], v[92:93], v[30:31]
	v_pk_mul_f32 v[28:29], v[116:117], v[28:29]
	v_pk_mul_f32 v[30:31], v[118:119], v[30:31]
	v_pk_mul_f32 v[44:45], v[44:45], v[56:57]
	v_pk_mul_f32 v[46:47], v[46:47], v[58:59]
	v_pk_mul_f32 v[52:53], v[52:53], v[56:57]
	v_pk_mul_f32 v[54:55], v[54:55], v[58:59]
	s_cbranch_scc1 .LBB0_253
	s_ashr_i32 s0, s12, 3
	s_and_b32 s10, s0, -16
	v_or_b32_e32 v56, s10, v96
	v_mul_lo_u32 v56, v56, s1
	v_lshlrev_b32_e32 v108, 1, v64
	v_add3_u32 v68, 16, v56, v108
	ds_read_b128 v[56:59], v68
	ds_read_b128 v[60:63], v68 offset:64
	ds_read_b128 v[64:67], v68 offset:128
	ds_read_b128 v[68:71], v68 offset:192
	s_add_u32 s0, s62, s28
	s_addc_u32 s1, s63, 0
	v_and_or_b32 v110, s9, 32, v96
	s_lshl_b32 s9, s9, 2
	v_mov_b32_e32 v83, v157
	s_and_b32 s9, s9, 0x80
	v_lshl_add_u64 v[88:89], v[72:73], 0, v[82:83]
	v_lshl_or_b32 v72, v95, 2, s10
	s_add_i32 s9, s9, 16
	v_lshl_add_u64 v[90:91], v[74:75], 0, v[82:83]
	s_movk_i32 s11, 0x90
	v_or_b32_e32 v73, 16, v110
	s_add_i32 s10, 16, 0x23800
	v_or_b32_e32 v74, 1, v72
	v_or_b32_e32 v75, 2, v72
	v_or_b32_e32 v77, 3, v72
	s_add_i32 s9, s9, 0x23400
	v_lshl_add_u64 v[86:87], s[0:1], 0, v[156:157]
	v_lshl_add_u64 v[92:93], v[78:79], 0, v[82:83]
	v_lshl_add_u64 v[84:85], v[84:85], 0, v[82:83]
	v_mul_lo_u32 v109, v97, s11
	v_mul_u32_u24_e32 v111, 0x110, v110
	v_cmp_le_i32_e64 s[0:1], v110, v72
	v_lshl_add_u32 v112, v72, 2, s10
	v_mul_lo_u32 v113, v72, s11
	v_cmp_le_i32_e64 s[38:39], v110, v74
	v_lshl_add_u32 v114, v74, 2, s10
	v_cmp_le_i32_e64 s[40:41], v110, v75
	v_lshl_add_u32 v115, v75, 2, s10
	v_cmp_le_i32_e64 s[42:43], v110, v77
	v_lshl_add_u32 v116, v77, 2, s10
	v_cmp_le_i32_e64 s[44:45], v73, v72
	v_cmp_le_i32_e64 s[46:47], v73, v74
	v_cmp_le_i32_e64 s[48:49], v73, v75
	v_cmp_le_i32_e64 s[50:51], v73, v77
	v_mul_u32_u24_e32 v117, 0x90, v96
	v_mul_lo_u32 v118, v76, s11
	s_add_i32 s8, s8, 64
	s_add_i32 s20, s18, 1
	v_lshl_add_u32 v119, v96, 2, s9
	v_mov_b32_e32 v83, 0
	ds_read_b32 v145, v112
	ds_read_b32 v146, v114
	ds_read_b32 v147, v115
	ds_read_b32 v158, v116
	s_waitcnt lgkmcnt(0)
	s_branch .LBB0_231

.LBB0_233:
	s_and_b32 s21, s19, 1
	s_mul_i32 s9, s21, 0xd400
	v_add_u32_e32 v120, s9, v107
	v_add_u32_e32 v121, v120, v111
	ds_read_b128 v[168:171], v121 offset:17408
	ds_read_b128 v[172:175], v121 offset:17472
	ds_read_b128 v[176:179], v121 offset:21760
	ds_read_b128 v[238:241], v121 offset:21824
	ds_read_b128 v[242:245], v121 offset:17536
	ds_read_b128 v[246:249], v121 offset:21888
	ds_read_b128 v[72:75], v121 offset:17600
	ds_read_b128 v[122:125], v121 offset:21952
	ds_read_b32 v130, v119
	ds_read_b32 v131, v119 offset:64
	s_waitcnt lgkmcnt(9)
	v_mfma_f32_16x16x32_bf16 v[76:79], v[56:59], v[168:171], 0
	s_waitcnt lgkmcnt(7)
	v_mfma_f32_16x16x32_bf16 v[126:129], v[56:59], v[176:179], 0
	s_waitcnt lgkmcnt(7)
	v_mfma_f32_16x16x32_bf16 v[76:79], v[60:63], v[172:175], v[76:79]
	s_waitcnt lgkmcnt(6)
	v_mfma_f32_16x16x32_bf16 v[126:129], v[60:63], v[238:241], v[126:129]
	s_waitcnt lgkmcnt(5)
	v_mfma_f32_16x16x32_bf16 v[76:79], v[64:67], v[242:245], v[76:79]
	s_waitcnt lgkmcnt(4)
	v_mfma_f32_16x16x32_bf16 v[126:129], v[64:67], v[246:249], v[126:129]
	s_waitcnt lgkmcnt(3)
	v_mfma_f32_16x16x32_bf16 v[76:79], v[68:71], v[72:75], v[76:79]
	s_waitcnt lgkmcnt(2)
	v_mfma_f32_16x16x32_bf16 v[126:129], v[68:71], v[122:125], v[126:129]
	s_waitcnt lgkmcnt(0)
	v_sub_f32_e32 v132, v130, v145
	v_sub_f32_e32 v133, v130, v146
	v_sub_f32_e32 v134, v130, v147
	v_sub_f32_e32 v135, v130, v158
	v_sub_f32_e32 v72, v131, v145
	v_sub_f32_e32 v73, v131, v146
	v_sub_f32_e32 v74, v131, v147
	v_sub_f32_e32 v75, v131, v158
	v_min_f32_e32 v132, 0, v132
	v_min_f32_e32 v133, 0, v133
	v_min_f32_e32 v134, 0, v134
	v_min_f32_e32 v135, 0, v135
	v_min_f32_e32 v72, 0, v72
	v_min_f32_e32 v73, 0, v73
	v_min_f32_e32 v74, 0, v74
	v_min_f32_e32 v75, 0, v75
	v_mul_f32_e32 v132, 0x3fb8aa3b, v132
	v_mul_f32_e32 v133, 0x3fb8aa3b, v133
	v_mul_f32_e32 v134, 0x3fb8aa3b, v134
	v_mul_f32_e32 v135, 0x3fb8aa3b, v135
	v_mul_f32_e32 v72, 0x3fb8aa3b, v72
	v_mul_f32_e32 v73, 0x3fb8aa3b, v73
	v_mul_f32_e32 v74, 0x3fb8aa3b, v74
	v_mul_f32_e32 v75, 0x3fb8aa3b, v75
	v_exp_f32_e32 v132, v132
	v_exp_f32_e32 v133, v133
	v_exp_f32_e32 v134, v134
	v_exp_f32_e32 v135, v135
	v_exp_f32_e32 v72, v72
	v_exp_f32_e32 v73, v73
	v_exp_f32_e32 v74, v74
	v_exp_f32_e32 v75, v75
	v_mul_f32_e32 v132, v76, v132
	v_mul_f32_e32 v133, v77, v133
	v_mul_f32_e32 v134, v78, v134
	v_mul_f32_e32 v135, v79, v135
	v_mul_f32_e32 v72, v126, v72
	v_mul_f32_e32 v73, v127, v73
	v_mul_f32_e32 v74, v128, v74
	v_mul_f32_e32 v75, v129, v75
	s_or_b64 s[22:23], s[0:1], s[10:11]
	v_cndmask_b32_e64 v132, 0, v132, s[22:23]
	s_or_b64 s[12:13], s[38:39], s[10:11]
	v_cndmask_b32_e64 v133, 0, v133, s[12:13]
	s_or_b64 s[22:23], s[40:41], s[10:11]
	v_cndmask_b32_e64 v134, 0, v134, s[22:23]
	s_or_b64 s[12:13], s[42:43], s[10:11]
	v_cndmask_b32_e64 v135, 0, v135, s[12:13]
	s_or_b64 s[22:23], s[44:45], s[10:11]
	v_cndmask_b32_e64 v72, 0, v72, s[22:23]
	s_or_b64 s[12:13], s[46:47], s[10:11]
	v_cndmask_b32_e64 v73, 0, v73, s[12:13]
	s_or_b64 s[22:23], s[48:49], s[10:11]
	v_cndmask_b32_e64 v74, 0, v74, s[22:23]
	s_or_b64 s[12:13], s[50:51], s[10:11]
	v_cndmask_b32_e64 v75, 0, v75, s[12:13]
	s_mul_i32 s9, s21, 0x2400
	s_add_i32 s9, s9, 16
	s_add_i32 s9, s9, 0x1ec00
	v_lshl_add_u32 v76, v110, 1, s9
	v_add_u32_e32 v76, v76, v113
	v_cvt_pk_bf16_f32 v132, v132, v132
	v_cvt_pk_bf16_f32 v133, v133, v133
	v_cvt_pk_bf16_f32 v134, v134, v134
	v_cvt_pk_bf16_f32 v135, v135, v135
	v_cvt_pk_bf16_f32 v72, v72, v72
	v_cvt_pk_bf16_f32 v73, v73, v73
	v_cvt_pk_bf16_f32 v74, v74, v74
	v_cvt_pk_bf16_f32 v75, v75, v75
	ds_write_b16 v76, v132
	ds_write_b16 v76, v133 offset:144
	ds_write_b16 v76, v134 offset:288
	ds_write_b16 v76, v135 offset:432
	ds_write_b16 v76, v72 offset:32
	ds_write_b16 v76, v73 offset:176
	ds_write_b16 v76, v74 offset:320
	ds_write_b16 v76, v75 offset:464
	s_andn2_b64 vcc, exec, s[10:11]
	s_waitcnt lgkmcnt(0)
	s_barrier
	s_cbranch_vccnz .LBB0_251
	s_xor_b32 s10, s21, 1
	s_mul_i32 s10, s10, 0xd400
	s_add_i32 s10, s10, 16
	v_add3_u32 v72, s10, v105, v156
	s_waitcnt vmcnt(5)
	ds_write_b128 v72, v[0:3] offset:17408
	s_waitcnt vmcnt(4)
	ds_write_b128 v72, v[4:7] offset:26112
	v_add3_u32 v72, s10, v106, v82
	s_waitcnt vmcnt(3)
	ds_write_b128 v72, v[8:11] offset:34816
	s_waitcnt vmcnt(2)
	ds_write_b128 v72, v[12:15] offset:44032
	s_waitcnt vmcnt(1)
	ds_write_b128 v72, v[16:19] offset:53248
	s_waitcnt vmcnt(0)
	ds_write_b128 v72, v[20:23] offset:62464
